# all five small-tile GEMM K loops: exact counted vmcnt waits (P3,P4,P6,P7,P8), on v25
# speedup vs baseline: 1.0058x; 1.0058x over previous
; #define SG_LOAD(kc, sg) do { _Pragma("unroll") for (int i_ = 0; i_ < 4; ++i_) { const int idx_ = tid + 512 * i_; \
;             ra[sg][i_] = *(const u32x4*)(A + (size_t)(row0 + (idx_ >> 5)) * ld + (kc) * 256 + (idx_ & 31) * 8); if (NC == 64 || i_ < 2) rb[sg][i_] = *(const u32x4*)(Bt + (size_t)(col0 + (idx_ >> 5)) * ld + (kc) * 256 + (idx_ & 31) * 8); } } while (0)
; template <int NC, class Epi>
; __device__ __forceinline__ void small_gemm_phase(LAS unsigned char* lds, const bf16_t* A, const bf16_t* Bt, int K, int ld, int ncolt  , const Epi& E, int first, int nblk, int bid, int tid) {
;     ...
;         u32x4 ra[2][4], rb[2][4];
;     ...
;         SG_LOAD(0, 0); SG_LOAD(1, 1);
;         f32x4 acc0 = {0.f, 0.f, 0.f, 0.f}, acc1 = {0.f, 0.f, 0.f, 0.f};
.LBB0_720:
	s_lshl_b32 s8, s5, 6
	s_and_b32 s11, s8, 0x1c0
	s_bitset1_b32 s11, 14
	s_lshl_b32 s8, s5, 2
	v_or_b32_e32 v0, s11, v148
	s_and_b32 s10, s8, 0x7fffffe0
	v_lshlrev_b32_e32 v52, 11, v0
	v_lshl_add_u64 v[58:59], v[54:55], 0, v[52:53]
	v_or_b32_e32 v52, s10, v148
	v_lshlrev_b64 v[0:1], 11, v[52:53]
	v_lshl_add_u64 v[60:61], v[56:57], 0, v[0:1]
	v_or_b32_e32 v0, s11, v79
	v_lshlrev_b32_e32 v52, 11, v0
	v_lshl_add_u64 v[62:63], v[54:55], 0, v[52:53]
	v_add_u32_e32 v52, s10, v79
	v_lshlrev_b64 v[0:1], 11, v[52:53]
	v_lshl_add_u64 v[64:65], v[56:57], 0, v[0:1]
	v_or_b32_e32 v0, s11, v80
	v_lshlrev_b32_e32 v52, 11, v0
	v_lshl_add_u64 v[66:67], v[54:55], 0, v[52:53]
	v_add_lshl_u32 v52, s11, v81, 11
	v_lshl_add_u64 v[68:69], v[54:55], 0, v[52:53]
	s_waitcnt lgkmcnt(0)
	global_load_dwordx4 v[0:3], v[58:59], off
	global_load_dwordx4 v[8:11], v[60:61], off
	global_load_dwordx4 v[16:19], v[62:63], off
	global_load_dwordx4 v[24:27], v[64:65], off
	global_load_dwordx4 v[32:35], v[66:67], off
	global_load_dwordx4 v[40:43], v[68:69], off
	global_load_dwordx4 v[4:7], v[58:59], off offset:512
	global_load_dwordx4 v[12:15], v[60:61], off offset:512
	global_load_dwordx4 v[20:23], v[62:63], off offset:512
	global_load_dwordx4 v[28:31], v[64:65], off offset:512
	global_load_dwordx4 v[36:39], v[66:67], off offset:512
	global_load_dwordx4 v[44:47], v[68:69], off offset:512
	s_mov_b64 s[8:9], -1
	v_mov_b32_e32 v48, 0
	v_mov_b32_e32 v49, v53
	v_mov_b32_e32 v50, v53
	v_mov_b32_e32 v51, v53
	s_branch .LBB0_722

; #define LAS __attribute__((address_space(3)))
; #define SG_LOAD(kc, sg) do { _Pragma("unroll") for (int i_ = 0; i_ < 4; ++i_) { const int idx_ = tid + 512 * i_; \
;             ra[sg][i_] = *(const u32x4*)(A + (size_t)(row0 + (idx_ >> 5)) * ld + (kc) * 256 + (idx_ & 31) * 8); if (NC == 64 || i_ < 2) rb[sg][i_] = *(const u32x4*)(Bt + (size_t)(col0 + (idx_ >> 5)) * ld + (kc) * 256 + (idx_ & 31) * 8); } } while (0)
; template <int NC, class Epi>
; __device__ __forceinline__ void small_gemm_phase(LAS unsigned char* lds, const bf16_t* A, const bf16_t* Bt, int K, int ld, int ncolt  , const Epi& E, int first, int nblk, int bid, int tid) {
;     ...
;         SG_LOAD(0, 0); SG_LOAD(1, 1);
;         f32x4 acc0 = {0.f, 0.f, 0.f, 0.f}, acc1 = {0.f, 0.f, 0.f, 0.f};
;         const LAS unsigned char* apl = lds + (16 * mt + fr) * SG_STRIDE + 16 * fq;
;         const LAS unsigned char* bpl = lds + SG_BOFF + ((NC / 2) * nh + fr) * SG_STRIDE + 16 * fq;
; #pragma unroll 1
;         for (int kc = 0; kc < nch; kc += 2) { SG_STEP(kc, 0); SG_STEP(kc + 1, 1); }
.LBB0_722:
	v_add_u32_e32 v52, v73, v82
	v_add_u32_e32 v100, v73, v83
	s_waitcnt vmcnt(11)
	ds_write_b128 v52, v[0:3]
	s_waitcnt vmcnt(10)
	ds_write_b128 v52, v[8:11] offset:33792
	s_waitcnt vmcnt(9)
	ds_write_b128 v100, v[16:19]
	s_waitcnt vmcnt(8)
	ds_write_b128 v100, v[24:27] offset:33792
	s_waitcnt vmcnt(7)
	ds_write_b128 v52, v[32:35] offset:16896
	v_add_u32_e32 v52, v73, v84
	s_and_b64 vcc, exec, s[8:9]
	s_waitcnt vmcnt(6)
	ds_write_b128 v52, v[40:43]
	s_cbranch_vccz .Lsgw_p3_last
	global_load_dwordx4 v[0:3], v[58:59], off offset:1024
	global_load_dwordx4 v[8:11], v[60:61], off offset:1024
	global_load_dwordx4 v[16:19], v[62:63], off offset:1024
	global_load_dwordx4 v[24:27], v[64:65], off offset:1024
	global_load_dwordx4 v[32:35], v[66:67], off offset:1024
	global_load_dwordx4 v[40:43], v[68:69], off offset:1024
.LBB0_724:
	s_waitcnt lgkmcnt(0)
	s_barrier
	ds_read_b128 v[100:103], v72 offset:33792
	ds_read_b128 v[104:107], v71
	ds_read_b128 v[108:111], v72 offset:33856
	ds_read_b128 v[112:115], v71 offset:64
	ds_read_b128 v[116:119], v71 offset:128
	ds_read_b128 v[120:123], v71 offset:192
	s_waitcnt lgkmcnt(4)
	v_mfma_f32_16x16x32_bf16 v[48:51], v[100:103], v[104:107], v[48:51]
	ds_read_b128 v[100:103], v72 offset:33920
	ds_read_b128 v[104:107], v72 offset:33984
	ds_read_b128 v[124:127], v71 offset:256
	ds_read_b128 v[128:131], v71 offset:320
	v_add_u32_e32 v52, v74, v82
	s_andn2_b64 vcc, exec, s[8:9]
	s_waitcnt lgkmcnt(6)
	v_mfma_f32_16x16x32_bf16 v[48:51], v[108:111], v[112:115], v[48:51]
	ds_read_b128 v[108:111], v72 offset:34048
	ds_read_b128 v[112:115], v72 offset:34112
	ds_read_b128 v[132:135], v71 offset:384
	ds_read_b128 v[136:139], v71 offset:448
	s_waitcnt lgkmcnt(7)
	v_mfma_f32_16x16x32_bf16 v[48:51], v[100:103], v[116:119], v[48:51]
	ds_read_b128 v[100:103], v72 offset:34176
	ds_read_b128 v[116:119], v72 offset:34240
	s_waitcnt vmcnt(11)
	ds_write_b128 v52, v[4:7]
	s_waitcnt lgkmcnt(9)
	v_mfma_f32_16x16x32_bf16 v[48:51], v[104:107], v[120:123], v[48:51]
	v_add_u32_e32 v104, v75, v82
	s_waitcnt vmcnt(10)
	ds_write_b128 v104, v[12:15]
	v_add_u32_e32 v104, v74, v83
	s_waitcnt lgkmcnt(7)
	v_mfma_f32_16x16x32_bf16 v[48:51], v[108:111], v[124:127], v[48:51]
	s_waitcnt vmcnt(9)
	ds_write_b128 v104, v[20:23]
	v_add_u32_e32 v104, v75, v83
	s_waitcnt vmcnt(8)
	ds_write_b128 v104, v[28:31]
	s_waitcnt lgkmcnt(8)
	v_mfma_f32_16x16x32_bf16 v[48:51], v[112:115], v[128:131], v[48:51]
	s_waitcnt vmcnt(7)
	ds_write_b128 v52, v[36:39] offset:16896
	v_add_u32_e32 v52, v74, v84
	s_waitcnt vmcnt(6)
	ds_write_b128 v52, v[44:47]
	s_waitcnt lgkmcnt(7)
	v_mfma_f32_16x16x32_bf16 v[48:51], v[100:103], v[132:135], v[48:51]
	s_waitcnt lgkmcnt(6)
	v_mfma_f32_16x16x32_bf16 v[48:51], v[116:119], v[136:139], v[48:51]
	s_cbranch_vccnz .LBB0_721
	global_load_dwordx4 v[4:7], v[58:59], off offset:1536
	global_load_dwordx4 v[12:15], v[60:61], off offset:1536
	global_load_dwordx4 v[20:23], v[62:63], off offset:1536
	global_load_dwordx4 v[28:31], v[64:65], off offset:1536
	global_load_dwordx4 v[36:39], v[66:67], off offset:1536
	global_load_dwordx4 v[44:47], v[68:69], off offset:1536
	s_branch .LBB0_721

; #define SG_LOAD(kc, sg) do { _Pragma("unroll") for (int i_ = 0; i_ < 4; ++i_) { const int idx_ = tid + 512 * i_; \
;             ra[sg][i_] = *(const u32x4*)(A + (size_t)(row0 + (idx_ >> 5)) * ld + (kc) * 256 + (idx_ & 31) * 8); if (NC == 64 || i_ < 2) rb[sg][i_] = *(const u32x4*)(Bt + (size_t)(col0 + (idx_ >> 5)) * ld + (kc) * 256 + (idx_ & 31) * 8); } } while (0)
; template <int NC, class Epi>
; __device__ __forceinline__ void small_gemm_phase(LAS unsigned char* lds, const bf16_t* A, const bf16_t* Bt, int K, int ld, int ncolt  , const Epi& E, int first, int nblk, int bid, int tid) {
;     ...
;         u32x4 ra[2][4], rb[2][4];
;     ...
;         SG_LOAD(0, 0); SG_LOAD(1, 1);
;         f32x4 acc0 = {0.f, 0.f, 0.f, 0.f}, acc1 = {0.f, 0.f, 0.f, 0.f};
.LBB0_812:
	s_lshl_b32 s10, s3, 6
	s_and_b32 s13, s10, 0x1c0
	s_bitset1_b32 s13, 14
	s_lshl_b32 s10, s3, 2
	v_or_b32_e32 v0, s13, v180
	s_and_b32 s12, s10, 0x7fffffe0
	v_lshlrev_b32_e32 v52, 11, v0
	v_lshl_add_u64 v[58:59], v[54:55], 0, v[52:53]
	v_or_b32_e32 v52, s12, v180
	v_lshlrev_b64 v[0:1], 11, v[52:53]
	v_lshl_add_u64 v[60:61], v[56:57], 0, v[0:1]
	v_or_b32_e32 v0, s13, v79
	v_lshlrev_b32_e32 v52, 11, v0
	v_lshl_add_u64 v[62:63], v[54:55], 0, v[52:53]
	v_add_u32_e32 v52, s12, v79
	v_lshlrev_b64 v[0:1], 11, v[52:53]
	v_lshl_add_u64 v[64:65], v[56:57], 0, v[0:1]
	v_or_b32_e32 v0, s13, v80
	v_lshlrev_b32_e32 v52, 11, v0
	v_lshl_add_u64 v[66:67], v[54:55], 0, v[52:53]
	v_add_lshl_u32 v52, s13, v81, 11
	v_lshl_add_u64 v[68:69], v[54:55], 0, v[52:53]
	global_load_dwordx4 v[0:3], v[58:59], off
	global_load_dwordx4 v[8:11], v[60:61], off
	global_load_dwordx4 v[16:19], v[62:63], off
	global_load_dwordx4 v[24:27], v[64:65], off
	global_load_dwordx4 v[32:35], v[66:67], off
	global_load_dwordx4 v[40:43], v[68:69], off
	global_load_dwordx4 v[4:7], v[58:59], off offset:512
	global_load_dwordx4 v[12:15], v[60:61], off offset:512
	global_load_dwordx4 v[20:23], v[62:63], off offset:512
	global_load_dwordx4 v[28:31], v[64:65], off offset:512
	global_load_dwordx4 v[36:39], v[66:67], off offset:512
	global_load_dwordx4 v[44:47], v[68:69], off offset:512
	s_mov_b64 s[10:11], -1
	v_mov_b32_e32 v48, 0
	v_mov_b32_e32 v49, v53
	v_mov_b32_e32 v50, v53
	v_mov_b32_e32 v51, v53
	s_branch .LBB0_814

; #define LAS __attribute__((address_space(3)))
; #define SG_LOAD(kc, sg) do { _Pragma("unroll") for (int i_ = 0; i_ < 4; ++i_) { const int idx_ = tid + 512 * i_; \
;             ra[sg][i_] = *(const u32x4*)(A + (size_t)(row0 + (idx_ >> 5)) * ld + (kc) * 256 + (idx_ & 31) * 8); if (NC == 64 || i_ < 2) rb[sg][i_] = *(const u32x4*)(Bt + (size_t)(col0 + (idx_ >> 5)) * ld + (kc) * 256 + (idx_ & 31) * 8); } } while (0)
; template <int NC, class Epi>
; __device__ __forceinline__ void small_gemm_phase(LAS unsigned char* lds, const bf16_t* A, const bf16_t* Bt, int K, int ld, int ncolt  , const Epi& E, int first, int nblk, int bid, int tid) {
;     ...
;         SG_LOAD(0, 0); SG_LOAD(1, 1);
;         f32x4 acc0 = {0.f, 0.f, 0.f, 0.f}, acc1 = {0.f, 0.f, 0.f, 0.f};
;         const LAS unsigned char* apl = lds + (16 * mt + fr) * SG_STRIDE + 16 * fq;
;         const LAS unsigned char* bpl = lds + SG_BOFF + ((NC / 2) * nh + fr) * SG_STRIDE + 16 * fq;
; #pragma unroll 1
;         for (int kc = 0; kc < nch; kc += 2) { SG_STEP(kc, 0); SG_STEP(kc + 1, 1); }
.LBB0_814:
	v_add_u32_e32 v52, v73, v82
	v_add_u32_e32 v99, v73, v83
	s_waitcnt vmcnt(11)
	ds_write_b128 v52, v[0:3]
	s_waitcnt vmcnt(10)
	ds_write_b128 v52, v[8:11] offset:33792
	s_waitcnt vmcnt(9)
	ds_write_b128 v99, v[16:19]
	s_waitcnt vmcnt(8)
	ds_write_b128 v99, v[24:27] offset:33792
	s_waitcnt vmcnt(7)
	ds_write_b128 v52, v[32:35] offset:16896
	v_add_u32_e32 v52, v73, v84
	s_and_b64 vcc, exec, s[10:11]
	s_waitcnt vmcnt(6)
	ds_write_b128 v52, v[40:43]
	s_cbranch_vccz .Lsgw_p4_last
	global_load_dwordx4 v[0:3], v[58:59], off offset:1024
	global_load_dwordx4 v[8:11], v[60:61], off offset:1024
	global_load_dwordx4 v[16:19], v[62:63], off offset:1024
	global_load_dwordx4 v[24:27], v[64:65], off offset:1024
	global_load_dwordx4 v[32:35], v[66:67], off offset:1024
	global_load_dwordx4 v[40:43], v[68:69], off offset:1024
.LBB0_816:
	s_waitcnt lgkmcnt(0)
	s_barrier
	ds_read_b128 v[100:103], v72 offset:33792
	ds_read_b128 v[104:107], v71
	ds_read_b128 v[108:111], v72 offset:33856
	ds_read_b128 v[112:115], v71 offset:64
	ds_read_b128 v[116:119], v71 offset:128
	ds_read_b128 v[120:123], v71 offset:192
	s_waitcnt lgkmcnt(4)
	v_mfma_f32_16x16x32_bf16 v[48:51], v[100:103], v[104:107], v[48:51]
	ds_read_b128 v[100:103], v72 offset:33920
	ds_read_b128 v[104:107], v72 offset:33984
	ds_read_b128 v[124:127], v71 offset:256
	ds_read_b128 v[128:131], v71 offset:320
	v_add_u32_e32 v99, v75, v82
	v_add_u32_e32 v52, v74, v82
	s_waitcnt lgkmcnt(6)
	v_mfma_f32_16x16x32_bf16 v[48:51], v[108:111], v[112:115], v[48:51]
	ds_read_b128 v[108:111], v72 offset:34048
	ds_read_b128 v[112:115], v72 offset:34112
	ds_read_b128 v[132:135], v71 offset:384
	ds_read_b128 v[136:139], v71 offset:448
	s_andn2_b64 vcc, exec, s[10:11]
	s_waitcnt lgkmcnt(7)
	v_mfma_f32_16x16x32_bf16 v[48:51], v[100:103], v[116:119], v[48:51]
	ds_read_b128 v[100:103], v72 offset:34176
	ds_read_b128 v[116:119], v72 offset:34240
	s_waitcnt vmcnt(10)
	ds_write_b128 v99, v[12:15]
	v_add_u32_e32 v99, v74, v83
	s_waitcnt lgkmcnt(9)
	v_mfma_f32_16x16x32_bf16 v[48:51], v[104:107], v[120:123], v[48:51]
	s_waitcnt vmcnt(11)
	ds_write_b128 v52, v[4:7]
	s_waitcnt vmcnt(9)
	ds_write_b128 v99, v[20:23]
	v_add_u32_e32 v99, v75, v83
	s_waitcnt lgkmcnt(8)
	v_mfma_f32_16x16x32_bf16 v[48:51], v[108:111], v[124:127], v[48:51]
	s_waitcnt vmcnt(8)
	ds_write_b128 v99, v[28:31]
	s_waitcnt vmcnt(7)
	ds_write_b128 v52, v[36:39] offset:16896
	v_add_u32_e32 v52, v74, v84
	s_waitcnt lgkmcnt(9)
	v_mfma_f32_16x16x32_bf16 v[48:51], v[112:115], v[128:131], v[48:51]
	s_waitcnt vmcnt(6)
	ds_write_b128 v52, v[44:47]
	s_waitcnt lgkmcnt(7)
	v_mfma_f32_16x16x32_bf16 v[48:51], v[100:103], v[132:135], v[48:51]
	s_waitcnt lgkmcnt(6)
	v_mfma_f32_16x16x32_bf16 v[48:51], v[116:119], v[136:139], v[48:51]
	s_cbranch_vccnz .LBB0_813
	global_load_dwordx4 v[4:7], v[58:59], off offset:1536
	global_load_dwordx4 v[12:15], v[60:61], off offset:1536
	global_load_dwordx4 v[20:23], v[62:63], off offset:1536
	global_load_dwordx4 v[28:31], v[64:65], off offset:1536
	global_load_dwordx4 v[36:39], v[66:67], off offset:1536
	global_load_dwordx4 v[44:47], v[68:69], off offset:1536
	s_branch .LBB0_813

; #define SG_LOAD(kc, sg) do { _Pragma("unroll") for (int i_ = 0; i_ < 4; ++i_) { const int idx_ = tid + 512 * i_; \
;             ra[sg][i_] = *(const u32x4*)(A + (size_t)(row0 + (idx_ >> 5)) * ld + (kc) * 256 + (idx_ & 31) * 8); if (NC == 64 || i_ < 2) rb[sg][i_] = *(const u32x4*)(Bt + (size_t)(col0 + (idx_ >> 5)) * ld + (kc) * 256 + (idx_ & 31) * 8); } } while (0)
; template <int NC, class Epi>
; __device__ __forceinline__ void small_gemm_phase(LAS unsigned char* lds, const bf16_t* A, const bf16_t* Bt, int K, int ld, int ncolt  , const Epi& E, int first, int nblk, int bid, int tid) {
;     ...
;         u32x4 ra[2][4], rb[2][4];
;     ...
;         SG_LOAD(0, 0); SG_LOAD(1, 1);
;         f32x4 acc0 = {0.f, 0.f, 0.f, 0.f}, acc1 = {0.f, 0.f, 0.f, 0.f};
.LBB0_1039:
	s_lshl_b32 s12, s11, 6
	s_and_b32 s15, s12, 0x1c0
	s_bitset1_b32 s15, 14
	s_lshl_b32 s12, s11, 2
	v_or_b32_e32 v0, s15, v182
	s_and_b32 s14, s12, 0x7fffffe0
	v_lshlrev_b32_e32 v52, 11, v0
	v_lshl_add_u64 v[58:59], v[54:55], 0, v[52:53]
	v_or_b32_e32 v52, s14, v182
	v_lshlrev_b64 v[0:1], 11, v[52:53]
	v_lshl_add_u64 v[60:61], v[56:57], 0, v[0:1]
	v_or_b32_e32 v0, s15, v79
	v_lshlrev_b32_e32 v52, 11, v0
	v_lshl_add_u64 v[62:63], v[54:55], 0, v[52:53]
	v_add_u32_e32 v52, s14, v79
	v_lshlrev_b64 v[0:1], 11, v[52:53]
	v_lshl_add_u64 v[64:65], v[56:57], 0, v[0:1]
	v_or_b32_e32 v0, s15, v80
	v_lshlrev_b32_e32 v52, 11, v0
	v_lshl_add_u64 v[66:67], v[54:55], 0, v[52:53]
	v_add_lshl_u32 v52, s15, v81, 11
	v_lshl_add_u64 v[68:69], v[54:55], 0, v[52:53]
	s_waitcnt lgkmcnt(1)
	global_load_dwordx4 v[0:3], v[58:59], off
	s_waitcnt lgkmcnt(0)
	global_load_dwordx4 v[8:11], v[60:61], off
	global_load_dwordx4 v[16:19], v[62:63], off
	global_load_dwordx4 v[24:27], v[64:65], off
	global_load_dwordx4 v[32:35], v[66:67], off
	global_load_dwordx4 v[40:43], v[68:69], off
	global_load_dwordx4 v[4:7], v[58:59], off offset:512
	global_load_dwordx4 v[12:15], v[60:61], off offset:512
	global_load_dwordx4 v[20:23], v[62:63], off offset:512
	global_load_dwordx4 v[28:31], v[64:65], off offset:512
	global_load_dwordx4 v[36:39], v[66:67], off offset:512
	global_load_dwordx4 v[44:47], v[68:69], off offset:512
	s_mov_b64 s[12:13], -1
	v_mov_b32_e32 v48, 0
	v_mov_b32_e32 v49, v53
	v_mov_b32_e32 v50, v53
	v_mov_b32_e32 v51, v53
	s_branch .LBB0_1041

; #define LAS __attribute__((address_space(3)))
; #define SG_LOAD(kc, sg) do { _Pragma("unroll") for (int i_ = 0; i_ < 4; ++i_) { const int idx_ = tid + 512 * i_; \
;             ra[sg][i_] = *(const u32x4*)(A + (size_t)(row0 + (idx_ >> 5)) * ld + (kc) * 256 + (idx_ & 31) * 8); if (NC == 64 || i_ < 2) rb[sg][i_] = *(const u32x4*)(Bt + (size_t)(col0 + (idx_ >> 5)) * ld + (kc) * 256 + (idx_ & 31) * 8); } } while (0)
; template <int NC, class Epi>
; __device__ __forceinline__ void small_gemm_phase(LAS unsigned char* lds, const bf16_t* A, const bf16_t* Bt, int K, int ld, int ncolt  , const Epi& E, int first, int nblk, int bid, int tid) {
;     ...
;         SG_LOAD(0, 0); SG_LOAD(1, 1);
;         f32x4 acc0 = {0.f, 0.f, 0.f, 0.f}, acc1 = {0.f, 0.f, 0.f, 0.f};
;         const LAS unsigned char* apl = lds + (16 * mt + fr) * SG_STRIDE + 16 * fq;
;         const LAS unsigned char* bpl = lds + SG_BOFF + ((NC / 2) * nh + fr) * SG_STRIDE + 16 * fq;
; #pragma unroll 1
;         for (int kc = 0; kc < nch; kc += 2) { SG_STEP(kc, 0); SG_STEP(kc + 1, 1); }
.LBB0_1041:
	v_add_u32_e32 v52, v73, v82
	v_add_u32_e32 v100, v73, v83
	s_waitcnt vmcnt(11)
	ds_write_b128 v52, v[0:3]
	s_waitcnt vmcnt(10)
	ds_write_b128 v52, v[8:11] offset:33792
	s_waitcnt vmcnt(9)
	ds_write_b128 v100, v[16:19]
	s_waitcnt vmcnt(8)
	ds_write_b128 v100, v[24:27] offset:33792
	s_waitcnt vmcnt(7)
	ds_write_b128 v52, v[32:35] offset:16896
	v_add_u32_e32 v52, v73, v84
	s_and_b64 vcc, exec, s[12:13]
	s_waitcnt vmcnt(6)
	ds_write_b128 v52, v[40:43]
	s_cbranch_vccz .Lsgw_p6_last
	global_load_dwordx4 v[0:3], v[58:59], off offset:1024
	global_load_dwordx4 v[8:11], v[60:61], off offset:1024
	global_load_dwordx4 v[16:19], v[62:63], off offset:1024
	global_load_dwordx4 v[24:27], v[64:65], off offset:1024
	global_load_dwordx4 v[32:35], v[66:67], off offset:1024
	global_load_dwordx4 v[40:43], v[68:69], off offset:1024
.LBB0_1043:
	s_waitcnt lgkmcnt(0)
	s_barrier
	ds_read_b128 v[100:103], v72 offset:33792
	ds_read_b128 v[104:107], v71
	ds_read_b128 v[108:111], v72 offset:33856
	ds_read_b128 v[112:115], v71 offset:64
	ds_read_b128 v[116:119], v71 offset:128
	ds_read_b128 v[120:123], v71 offset:192
	s_waitcnt lgkmcnt(4)
	v_mfma_f32_16x16x32_bf16 v[48:51], v[100:103], v[104:107], v[48:51]
	ds_read_b128 v[100:103], v72 offset:33920
	ds_read_b128 v[104:107], v72 offset:33984
	ds_read_b128 v[124:127], v71 offset:256
	ds_read_b128 v[128:131], v71 offset:320
	v_add_u32_e32 v52, v74, v82
	s_andn2_b64 vcc, exec, s[12:13]
	s_waitcnt lgkmcnt(6)
	v_mfma_f32_16x16x32_bf16 v[48:51], v[108:111], v[112:115], v[48:51]
	ds_read_b128 v[108:111], v72 offset:34048
	ds_read_b128 v[112:115], v72 offset:34112
	ds_read_b128 v[132:135], v71 offset:384
	ds_read_b128 v[136:139], v71 offset:448
	s_waitcnt lgkmcnt(7)
	v_mfma_f32_16x16x32_bf16 v[48:51], v[100:103], v[116:119], v[48:51]
	ds_read_b128 v[100:103], v72 offset:34176
	ds_read_b128 v[116:119], v72 offset:34240
	s_waitcnt vmcnt(11)
	ds_write_b128 v52, v[4:7]
	s_waitcnt lgkmcnt(9)
	v_mfma_f32_16x16x32_bf16 v[48:51], v[104:107], v[120:123], v[48:51]
	v_add_u32_e32 v104, v75, v82
	s_waitcnt vmcnt(10)
	ds_write_b128 v104, v[12:15]
	v_add_u32_e32 v104, v74, v83
	s_waitcnt lgkmcnt(7)
	v_mfma_f32_16x16x32_bf16 v[48:51], v[108:111], v[124:127], v[48:51]
	s_waitcnt vmcnt(9)
	ds_write_b128 v104, v[20:23]
	v_add_u32_e32 v104, v75, v83
	s_waitcnt vmcnt(8)
	ds_write_b128 v104, v[28:31]
	s_waitcnt lgkmcnt(8)
	v_mfma_f32_16x16x32_bf16 v[48:51], v[112:115], v[128:131], v[48:51]
	s_waitcnt vmcnt(7)
	ds_write_b128 v52, v[36:39] offset:16896
	v_add_u32_e32 v52, v74, v84
	s_waitcnt vmcnt(6)
	ds_write_b128 v52, v[44:47]
	s_waitcnt lgkmcnt(7)
	v_mfma_f32_16x16x32_bf16 v[48:51], v[100:103], v[132:135], v[48:51]
	s_waitcnt lgkmcnt(6)
	v_mfma_f32_16x16x32_bf16 v[48:51], v[116:119], v[136:139], v[48:51]
	s_cbranch_vccnz .LBB0_1040
	global_load_dwordx4 v[4:7], v[58:59], off offset:1536
	global_load_dwordx4 v[12:15], v[60:61], off offset:1536
	global_load_dwordx4 v[20:23], v[62:63], off offset:1536
	global_load_dwordx4 v[28:31], v[64:65], off offset:1536
	global_load_dwordx4 v[36:39], v[66:67], off offset:1536
	global_load_dwordx4 v[44:47], v[68:69], off offset:1536
	s_branch .LBB0_1040

; #define SG_LOAD(kc, sg) do { _Pragma("unroll") for (int i_ = 0; i_ < 4; ++i_) { const int idx_ = tid + 512 * i_; \
;             ra[sg][i_] = *(const u32x4*)(A + (size_t)(row0 + (idx_ >> 5)) * ld + (kc) * 256 + (idx_ & 31) * 8); if (NC == 64 || i_ < 2) rb[sg][i_] = *(const u32x4*)(Bt + (size_t)(col0 + (idx_ >> 5)) * ld + (kc) * 256 + (idx_ & 31) * 8); } } while (0)
; template <int NC, class Epi>
; __device__ __forceinline__ void small_gemm_phase(LAS unsigned char* lds, const bf16_t* A, const bf16_t* Bt, int K, int ld, int ncolt  , const Epi& E, int first, int nblk, int bid, int tid) {
;     ...
;         u32x4 ra[2][4], rb[2][4];
;     ...
;         SG_LOAD(0, 0); SG_LOAD(1, 1);
;         f32x4 acc0 = {0.f, 0.f, 0.f, 0.f}, acc1 = {0.f, 0.f, 0.f, 0.f};
.LBB0_1131:
	s_lshl_b32 s2, s12, 6
	s_and_b32 s14, s2, 0x1c0
	s_bitset1_b32 s14, 14
	s_lshl_b32 s2, s12, 3
	v_or_b32_e32 v0, s14, v180
	s_and_b32 s13, s2, 0x7fffffc0
	v_lshlrev_b32_e32 v72, 11, v0
	v_lshl_add_u64 v[78:79], v[74:75], 0, v[72:73]
	v_or_b32_e32 v72, s13, v180
	v_lshlrev_b64 v[0:1], 11, v[72:73]
	v_lshl_add_u64 v[80:81], v[76:77], 0, v[0:1]
	v_or_b32_e32 v0, s14, v104
	v_lshlrev_b32_e32 v72, 11, v0
	v_lshl_add_u64 v[82:83], v[74:75], 0, v[72:73]
	v_or_b32_e32 v72, s13, v104
	v_lshlrev_b64 v[0:1], 11, v[72:73]
	v_lshl_add_u64 v[84:85], v[76:77], 0, v[0:1]
	v_or_b32_e32 v0, s14, v105
	v_lshlrev_b32_e32 v72, 11, v0
	v_lshl_add_u64 v[86:87], v[74:75], 0, v[72:73]
	v_or_b32_e32 v72, s13, v105
	v_lshlrev_b64 v[0:1], 11, v[72:73]
	v_add_lshl_u32 v72, s14, v106, 11
	v_lshl_add_u64 v[90:91], v[74:75], 0, v[72:73]
	v_add_u32_e32 v72, s13, v106
	v_lshl_add_u64 v[88:89], v[76:77], 0, v[0:1]
	v_lshlrev_b64 v[0:1], 11, v[72:73]
	v_lshl_add_u64 v[92:93], v[76:77], 0, v[0:1]
	global_load_dwordx4 v[0:3], v[78:79], off
	global_load_dwordx4 v[8:11], v[80:81], off
	global_load_dwordx4 v[16:19], v[82:83], off
	global_load_dwordx4 v[24:27], v[84:85], off
	global_load_dwordx4 v[32:35], v[86:87], off
	global_load_dwordx4 v[40:43], v[88:89], off
	global_load_dwordx4 v[48:51], v[90:91], off
	global_load_dwordx4 v[56:59], v[92:93], off
	global_load_dwordx4 v[4:7], v[78:79], off offset:512
	global_load_dwordx4 v[12:15], v[80:81], off offset:512
	global_load_dwordx4 v[20:23], v[82:83], off offset:512
	global_load_dwordx4 v[28:31], v[84:85], off offset:512
	global_load_dwordx4 v[36:39], v[86:87], off offset:512
	global_load_dwordx4 v[44:47], v[88:89], off offset:512
	global_load_dwordx4 v[52:55], v[90:91], off offset:512
	global_load_dwordx4 v[60:63], v[92:93], off offset:512
	s_mov_b64 s[2:3], -1
	v_mov_b32_e32 v68, 0
	v_mov_b32_e32 v69, v73
	v_mov_b32_e32 v70, v73
	v_mov_b32_e32 v71, v73
	v_mov_b32_e32 v64, 0
	v_mov_b32_e32 v65, v73
	v_mov_b32_e32 v66, v73
	v_mov_b32_e32 v67, v73
	s_branch .LBB0_1133

; #define LAS __attribute__((address_space(3)))
; #define SG_LOAD(kc, sg) do { _Pragma("unroll") for (int i_ = 0; i_ < 4; ++i_) { const int idx_ = tid + 512 * i_; \
;             ra[sg][i_] = *(const u32x4*)(A + (size_t)(row0 + (idx_ >> 5)) * ld + (kc) * 256 + (idx_ & 31) * 8); if (NC == 64 || i_ < 2) rb[sg][i_] = *(const u32x4*)(Bt + (size_t)(col0 + (idx_ >> 5)) * ld + (kc) * 256 + (idx_ & 31) * 8); } } while (0)
; template <int NC, class Epi>
; __device__ __forceinline__ void small_gemm_phase(LAS unsigned char* lds, const bf16_t* A, const bf16_t* Bt, int K, int ld, int ncolt  , const Epi& E, int first, int nblk, int bid, int tid) {
;     ...
;         SG_LOAD(0, 0); SG_LOAD(1, 1);
;         f32x4 acc0 = {0.f, 0.f, 0.f, 0.f}, acc1 = {0.f, 0.f, 0.f, 0.f};
;         const LAS unsigned char* apl = lds + (16 * mt + fr) * SG_STRIDE + 16 * fq;
;         const LAS unsigned char* bpl = lds + SG_BOFF + ((NC / 2) * nh + fr) * SG_STRIDE + 16 * fq;
; #pragma unroll 1
;         for (int kc = 0; kc < nch; kc += 2) { SG_STEP(kc, 0); SG_STEP(kc + 1, 1); }
.LBB0_1133:
	v_add_u32_e32 v72, v97, v107
	v_add_u32_e32 v131, v97, v108
	s_waitcnt vmcnt(15)
	ds_write_b128 v72, v[0:3]
	s_waitcnt vmcnt(14)
	ds_write_b128 v72, v[8:11] offset:33792
	s_waitcnt vmcnt(13)
	ds_write_b128 v131, v[16:19]
	s_waitcnt vmcnt(12)
	ds_write_b128 v131, v[24:27] offset:33792
	s_waitcnt vmcnt(11)
	ds_write_b128 v72, v[32:35] offset:16896
	s_waitcnt vmcnt(10)
	ds_write_b128 v72, v[40:43] offset:50688
	v_add_u32_e32 v72, v97, v109
	s_and_b64 vcc, exec, s[2:3]
	s_waitcnt vmcnt(9)
	ds_write_b128 v72, v[48:51]
	s_waitcnt vmcnt(8)
	ds_write_b128 v72, v[56:59] offset:33792
	s_cbranch_vccz .Lsgw_p7_last
	global_load_dwordx4 v[0:3], v[78:79], off offset:1024
	global_load_dwordx4 v[8:11], v[80:81], off offset:1024
	global_load_dwordx4 v[16:19], v[82:83], off offset:1024
	global_load_dwordx4 v[24:27], v[84:85], off offset:1024
	global_load_dwordx4 v[32:35], v[86:87], off offset:1024
	global_load_dwordx4 v[40:43], v[88:89], off offset:1024
	global_load_dwordx4 v[48:51], v[90:91], off offset:1024
	global_load_dwordx4 v[56:59], v[92:93], off offset:1024
.LBB0_1135:
	s_waitcnt lgkmcnt(0)
	s_barrier
	ds_read_b128 v[132:135], v96 offset:33792
	ds_read_b128 v[136:139], v95
	ds_read_b128 v[140:143], v95 offset:64
	ds_read_b128 v[144:147], v96 offset:33856
	s_waitcnt lgkmcnt(2)
	v_mfma_f32_16x16x32_bf16 v[68:71], v[132:135], v[136:139], v[68:71]
	ds_read_b128 v[132:135], v96 offset:42240
	ds_read_b128 v[148:151], v96 offset:42304
	v_add_u32_e32 v72, v98, v107
	v_add_u32_e32 v131, v99, v107
	s_waitcnt lgkmcnt(1)
	v_mfma_f32_16x16x32_bf16 v[64:67], v[132:135], v[136:139], v[64:67]
	ds_read_b128 v[132:135], v96 offset:33920
	s_andn2_b64 vcc, exec, s[2:3]
	v_mfma_f32_16x16x32_bf16 v[68:71], v[144:147], v[140:143], v[68:71]
	s_waitcnt lgkmcnt(1)
	v_mfma_f32_16x16x32_bf16 v[64:67], v[148:151], v[140:143], v[64:67]
	ds_read_b128 v[136:139], v95 offset:128
	ds_read_b128 v[140:143], v95 offset:192
	ds_read_b128 v[144:147], v96 offset:33984
	s_waitcnt lgkmcnt(2)
	v_mfma_f32_16x16x32_bf16 v[68:71], v[132:135], v[136:139], v[68:71]
	ds_read_b128 v[132:135], v96 offset:42368
	ds_read_b128 v[148:151], v96 offset:42432
	s_waitcnt lgkmcnt(1)
	v_mfma_f32_16x16x32_bf16 v[64:67], v[132:135], v[136:139], v[64:67]
	v_mfma_f32_16x16x32_bf16 v[68:71], v[144:147], v[140:143], v[68:71]
	ds_read_b128 v[132:135], v96 offset:34048
	ds_read_b128 v[136:139], v95 offset:256
	ds_read_b128 v[144:147], v96 offset:42496
	s_waitcnt lgkmcnt(3)
	v_mfma_f32_16x16x32_bf16 v[64:67], v[148:151], v[140:143], v[64:67]
	ds_read_b128 v[140:143], v95 offset:320
	ds_read_b128 v[148:151], v96 offset:34112
	ds_read_b128 v[152:155], v96 offset:42560
	s_waitcnt lgkmcnt(4)
	v_mfma_f32_16x16x32_bf16 v[68:71], v[132:135], v[136:139], v[68:71]
	ds_read_b128 v[132:135], v95 offset:384
	ds_read_b128 v[156:159], v95 offset:448
	ds_read_b128 v[160:163], v96 offset:34176
	ds_read_b128 v[164:167], v96 offset:34240
	s_waitcnt lgkmcnt(7)
	v_mfma_f32_16x16x32_bf16 v[64:67], v[144:147], v[136:139], v[64:67]
	ds_read_b128 v[136:139], v96 offset:42624
	ds_read_b128 v[144:147], v96 offset:42688
	s_waitcnt vmcnt(15)
	ds_write_b128 v72, v[4:7]
	s_waitcnt vmcnt(14)
	ds_write_b128 v131, v[12:15]
	s_waitcnt lgkmcnt(9)
	v_mfma_f32_16x16x32_bf16 v[68:71], v[148:151], v[140:143], v[68:71]
	v_add_u32_e32 v148, v98, v108
	s_waitcnt vmcnt(13)
	ds_write_b128 v148, v[20:23]
	s_waitcnt lgkmcnt(9)
	v_mfma_f32_16x16x32_bf16 v[64:67], v[152:155], v[140:143], v[64:67]
	v_add_u32_e32 v140, v99, v108
	s_waitcnt vmcnt(12)
	ds_write_b128 v140, v[28:31]
	s_waitcnt vmcnt(11)
	ds_write_b128 v72, v[36:39] offset:16896
	s_waitcnt vmcnt(10)
	ds_write_b128 v131, v[44:47] offset:16896
	s_waitcnt lgkmcnt(9)
	v_mfma_f32_16x16x32_bf16 v[68:71], v[160:163], v[132:135], v[68:71]
	v_add_u32_e32 v72, v98, v109
	s_waitcnt vmcnt(9)
	ds_write_b128 v72, v[52:55]
	s_waitcnt lgkmcnt(8)
	v_mfma_f32_16x16x32_bf16 v[132:135], v[136:139], v[132:135], v[64:67]
	s_nop 2
	v_add_u32_e32 v64, v99, v109
	s_waitcnt vmcnt(8)
	ds_write_b128 v64, v[60:63]
	v_mfma_f32_16x16x32_bf16 v[64:67], v[164:167], v[156:159], v[68:71]
	s_waitcnt lgkmcnt(8)
	v_mfma_f32_16x16x32_bf16 v[68:71], v[144:147], v[156:159], v[132:135]
	s_cbranch_vccnz .LBB0_1132
	global_load_dwordx4 v[4:7], v[78:79], off offset:1536
	global_load_dwordx4 v[12:15], v[80:81], off offset:1536
	global_load_dwordx4 v[20:23], v[82:83], off offset:1536
	global_load_dwordx4 v[28:31], v[84:85], off offset:1536
	global_load_dwordx4 v[36:39], v[86:87], off offset:1536
	global_load_dwordx4 v[44:47], v[88:89], off offset:1536
	global_load_dwordx4 v[52:55], v[90:91], off offset:1536
	global_load_dwordx4 v[60:63], v[92:93], off offset:1536
	s_branch .LBB0_1132
